# NAT attention: V^T fragments read with direct ds_read_b64 into the MFMA operand registers (removes 26 register moves and the staggered waits per tile)
# baseline (speedup 1.0000x reference)
.LBB0_510:
	s_lshl_b32 s72, s70, 14
	s_add_i32 s72, s72, 0
	v_add_u32_e32 v1, s72, v90
	v_add_u32_e32 v2, s72, v91
	ds_read_b128 v[28:31], v1
	ds_read_b128 v[32:35], v1 offset:2048
	ds_read_b128 v[36:39], v2
	ds_read_b128 v[40:43], v2 offset:2048
	ds_read_b128 v[44:47], v1 offset:4096
	ds_read_b128 v[48:51], v1 offset:6144
	ds_read_b128 v[52:55], v2 offset:4096
	ds_read_b128 v[56:59], v2 offset:6144
	s_waitcnt lgkmcnt(0)
	v_mfma_f32_16x16x32_bf16 v[28:31], v[28:31], v[4:7], 0
	v_add_u32_e32 v1, s72, v92
	v_add_u32_e32 v2, s72, v93
	v_mfma_f32_16x16x32_bf16 v[74:77], v[36:39], v[8:11], v[28:31]
	v_mfma_f32_16x16x32_bf16 v[28:31], v[32:35], v[4:7], 0
	v_mfma_f32_16x16x32_bf16 v[68:71], v[40:43], v[8:11], v[28:31]
	v_mfma_f32_16x16x32_bf16 v[28:31], v[44:47], v[4:7], 0
	v_mfma_f32_16x16x32_bf16 v[64:67], v[52:55], v[8:11], v[28:31]
	v_mfma_f32_16x16x32_bf16 v[28:31], v[48:51], v[4:7], 0
	v_mfma_f32_16x16x32_bf16 v[60:63], v[56:59], v[8:11], v[28:31]
	ds_read_b64 v[52:53], v1 offset:10240
	ds_read_b64 v[54:55], v2 offset:10240
	ds_read_b64 v[140:141], v1 offset:8192
	ds_read_b64 v[142:143], v2 offset:8192
	ds_read_b64 v[56:57], v1 offset:12288
	ds_read_b64 v[58:59], v2 offset:12288
	ds_read_b64 v[44:45], v1 offset:14336
	ds_read_b64 v[46:47], v2 offset:14336
	v_add_u32_e32 v1, s72, v96
	v_add_u32_e32 v2, s72, v97
	ds_read_b64 v[32:33], v1 offset:8192
	ds_read_b64 v[34:35], v2 offset:8192
	ds_read_b64 v[36:37], v1 offset:10240
	ds_read_b64 v[38:39], v2 offset:10240
	ds_read_b64 v[40:41], v1 offset:12288
	ds_read_b64 v[42:43], v2 offset:12288
	ds_read_b64 v[28:29], v1 offset:14336
	ds_read_b64 v[30:31], v2 offset:14336
	s_cmp_gt_u32 s71, 7
	s_mov_b32 s71, 0x3e38aa3b
	s_cbranch_scc1 .LBB0_544
	v_add_u32_e32 v1, s69, v98
	v_add_u32_e32 v1, 0x103a0, v1
	ds_read_b32 v102, v1
	ds_read_b32 v103, v1 offset:4
	ds_read_b32 v104, v1 offset:8
	ds_read_b32 v105, v1 offset:12
	ds_read_b32 v106, v1 offset:64
	ds_read_b32 v107, v1 offset:68
	ds_read_b32 v108, v1 offset:72
	ds_read_b32 v109, v1 offset:76
	ds_read_b32 v110, v1 offset:128
	ds_read_b32 v111, v1 offset:132
	ds_read_b32 v112, v1 offset:136
	ds_read_b32 v113, v1 offset:140
	ds_read_b32 v114, v1 offset:192
	ds_read_b32 v115, v1 offset:196
	ds_read_b32 v210, v1 offset:200
	ds_read_b32 v211, v1 offset:204
	v_mov_b32_e32 v2, 0xff800000
	s_mov_b32 s71, 1.0
	s_waitcnt lgkmcnt(15)
	v_mul_f32_e32 v3, s5, v102
	v_mul_f32_e32 v74, s4, v74
	v_add_f32_e32 v74, v74, v3
	v_cndmask_b32_e64 v74, v2, v74, s[40:41]
	s_waitcnt lgkmcnt(14)
	v_mul_f32_e32 v3, s5, v103
	v_mul_f32_e32 v75, s4, v75
	v_add_f32_e32 v75, v75, v3
	v_cndmask_b32_e64 v75, v2, v75, s[42:43]
	s_waitcnt lgkmcnt(13)
	v_mul_f32_e32 v3, s5, v104
	v_mul_f32_e32 v76, s4, v76
	v_add_f32_e32 v76, v76, v3
	v_cndmask_b32_e64 v76, v2, v76, s[44:45]
	s_waitcnt lgkmcnt(12)
	v_mul_f32_e32 v3, s5, v105
	v_mul_f32_e32 v77, s4, v77
	v_add_f32_e32 v77, v77, v3
	v_cndmask_b32_e64 v77, v2, v77, s[46:47]
	s_waitcnt lgkmcnt(11)
	v_mul_f32_e32 v3, s5, v106
	v_mul_f32_e32 v68, s4, v68
	v_add_f32_e32 v68, v68, v3
	v_cndmask_b32_e64 v68, v2, v68, s[28:29]
	s_waitcnt lgkmcnt(10)
	v_mul_f32_e32 v3, s5, v107
	v_mul_f32_e32 v69, s4, v69
	v_add_f32_e32 v69, v69, v3
	v_cndmask_b32_e64 v69, v2, v69, s[30:31]
	s_waitcnt lgkmcnt(9)
	v_mul_f32_e32 v3, s5, v108
	v_mul_f32_e32 v70, s4, v70
	v_add_f32_e32 v70, v70, v3
	v_cndmask_b32_e64 v70, v2, v70, s[34:35]
	s_waitcnt lgkmcnt(8)
	v_mul_f32_e32 v3, s5, v109
	v_mul_f32_e32 v71, s4, v71
	v_add_f32_e32 v71, v71, v3
	v_cndmask_b32_e64 v71, v2, v71, s[88:89]
	s_waitcnt lgkmcnt(7)
	v_mul_f32_e32 v3, s5, v110
	v_mul_f32_e32 v64, s4, v64
	v_add_f32_e32 v64, v64, v3
	v_cndmask_b32_e64 v64, v2, v64, s[12:13]
	s_waitcnt lgkmcnt(6)
	v_mul_f32_e32 v3, s5, v111
	v_mul_f32_e32 v65, s4, v65
	v_add_f32_e32 v65, v65, v3
	v_cndmask_b32_e64 v65, v2, v65, s[14:15]
	s_waitcnt lgkmcnt(5)
	v_mul_f32_e32 v3, s5, v112
	v_mul_f32_e32 v66, s4, v66
	v_add_f32_e32 v66, v66, v3
	v_cndmask_b32_e64 v66, v2, v66, s[60:61]
	s_waitcnt lgkmcnt(4)
	v_mul_f32_e32 v3, s5, v113
	v_mul_f32_e32 v67, s4, v67
	v_add_f32_e32 v67, v67, v3
	v_cndmask_b32_e64 v67, v2, v67, s[6:7]
	s_waitcnt lgkmcnt(3)
	v_mul_f32_e32 v3, s5, v114
	v_mul_f32_e32 v60, s4, v60
	v_add_f32_e32 v60, v60, v3
	v_cndmask_b32_e64 v60, v2, v60, s[48:49]
	s_waitcnt lgkmcnt(2)
	v_mul_f32_e32 v3, s5, v115
	v_mul_f32_e32 v61, s4, v61
	v_add_f32_e32 v61, v61, v3
	v_cndmask_b32_e64 v61, v2, v61, s[50:51]
	s_waitcnt lgkmcnt(1)
	v_mul_f32_e32 v3, s5, v210
	v_mul_f32_e32 v62, s4, v62
	v_add_f32_e32 v62, v62, v3
	v_cndmask_b32_e64 v62, v2, v62, s[52:53]
	s_waitcnt lgkmcnt(0)
	v_mul_f32_e32 v3, s5, v211
	v_mul_f32_e32 v63, s4, v63
	v_add_f32_e32 v63, v63, v3
	v_cndmask_b32_e64 v63, v2, v63, s[54:55]

.LBB0_546:
	v_fma_f32 v2, v74, s71, -v1
	v_exp_f32_e32 v2, v2
	v_fma_f32 v3, v75, s71, -v1
	v_exp_f32_e32 v3, v3
	v_fma_f32 v72, v76, s71, -v1
	v_exp_f32_e32 v72, v72
	v_fma_f32 v73, v77, s71, -v1
	v_exp_f32_e32 v73, v73
	v_fma_f32 v68, v68, s71, -v1
	v_add_f32_e32 v74, 0, v2
	v_exp_f32_e32 v75, v68
	v_fma_f32 v68, v69, s71, -v1
	v_add_f32_e32 v74, v3, v74
	v_exp_f32_e32 v76, v68
	v_fma_f32 v68, v70, s71, -v1
	v_add_f32_e32 v74, v72, v74
	v_exp_f32_e32 v77, v68
	v_fma_f32 v68, v71, s71, -v1
	v_add_f32_e32 v74, v73, v74
	v_exp_f32_e32 v71, v68
	v_fma_f32 v64, v64, s71, -v1
	v_add_f32_e32 v68, v75, v74
	v_exp_f32_e32 v74, v64
	v_fma_f32 v64, v65, s71, -v1
	v_add_f32_e32 v68, v76, v68
	v_exp_f32_e32 v78, v64
	v_fma_f32 v64, v66, s71, -v1
	v_add_f32_e32 v68, v77, v68
	v_exp_f32_e32 v79, v64
	v_fma_f32 v64, v67, s71, -v1
	v_add_f32_e32 v68, v71, v68
	v_exp_f32_e32 v100, v64
	v_add_f32_e32 v64, v74, v68
	v_add_f32_e32 v64, v78, v64
	v_add_f32_e32 v64, v79, v64
	s_waitcnt lgkmcnt(0)
	v_add_f32_e32 v101, v100, v64
	v_fma_f32 v60, s71, v60, -v1
	v_fma_f32 v61, s71, v61, -v1
	v_fma_f32 v62, s71, v62, -v1
	v_cvt_pk_bf16_f32 v68, v2, v3
	v_cvt_pk_bf16_f32 v69, v72, v73
	v_cvt_pk_bf16_f32 v70, v75, v76
	v_cvt_pk_bf16_f32 v71, v77, v71
	v_fma_f32 v2, s71, v63, -v1
	v_exp_f32_e32 v60, v60
	v_exp_f32_e32 v61, v61
	v_exp_f32_e32 v62, v62
	v_mfma_f32_16x16x32_bf16 v[20:23], v[52:55], v[68:71], v[20:23]
	v_exp_f32_e32 v2, v2
	v_mfma_f32_16x16x32_bf16 v[24:27], v[140:143], v[68:71], v[24:27]
	v_cvt_pk_bf16_f32 v48, v74, v78
	v_cvt_pk_bf16_f32 v49, v79, v100
	v_cvt_pk_bf16_f32 v50, v60, v61
	v_mfma_f32_16x16x32_bf16 v[16:19], v[56:59], v[68:71], v[16:19]
	v_cvt_pk_bf16_f32 v51, v62, v2
	v_add_f32_e32 v3, v60, v101
	v_add_f32_e32 v3, v61, v3
	v_mfma_f32_16x16x32_bf16 v[12:15], v[44:47], v[68:71], v[12:15]
	s_add_i32 s70, s70, 1
	v_add_f32_e32 v3, v62, v3
	s_cmp_lg_u32 s70, 4
	v_mfma_f32_16x16x32_bf16 v[24:27], v[32:35], v[48:51], v[24:27]
	v_add_f32_e32 v2, v2, v3
	s_cselect_b32 s70, s70, 0
	s_add_i32 s8, s8, -1
	v_mfma_f32_16x16x32_bf16 v[20:23], v[36:39], v[48:51], v[20:23]
	s_addk_i32 s69, 0x7c
	s_add_i32 s64, s64, 1
	s_cmp_lg_u32 s68, s69
	v_mfma_f32_16x16x32_bf16 v[16:19], v[40:43], v[48:51], v[16:19]
	v_add_f32_e32 v99, v2, v99
	v_mfma_f32_16x16x32_bf16 v[12:15], v[28:31], v[48:51], v[12:15]
	s_cbranch_scc0 .LBB0_549
	v_mov_b32_e32 v100, v1
	s_cmp_lt_i32 s8, 2
	s_mov_b64 vcc, -1
	s_cbranch_scc1 .LBB0_501
	s_branch .LBB0_506
